# C2 conv epilogue shuffles also by DPP row rotate (on top of the FFN-F2 DPP version)
# baseline (speedup 1.0000x reference)
.LBB0_211:
	s_lshl_b32 s0, s22, 8
	s_add_i32 s0, s0, s39
	s_cmpk_lt_i32 s0, 0x2000
	s_movk_i32 s51, 0xfff
	v_lshl_or_b32 v174, s2, 8, v198
	s_cselect_b32 s2, s51, 0x7ff
	s_or_b32 s12, s0, 63
	s_and_b32 s1, s2, s0
	s_and_b32 s26, s2, s12
	v_or_b32_e32 v194, s0, v196
	s_cmp_eq_u32 s1, 0
	v_ashrrev_i32_e32 v195, 31, v194
	s_cselect_b64 s[12:13], -1, 0
	s_ashr_i32 s1, s0, 31
	v_ashrrev_i32_e32 v175, 31, v174
	v_lshlrev_b64 v[208:209], 12, v[194:195]
	s_lshl_b64 s[14:15], s[0:1], 12
	v_lshl_add_u64 v[120:121], s[30:31], 0, v[208:209]
	v_lshlrev_b64 v[182:183], 1, v[174:175]
	s_add_u32 s14, s30, s14
	v_lshl_add_u64 v[178:179], v[120:121], 0, v[182:183]
	s_addc_u32 s15, s31, s15
	v_add_co_u32_e32 v180, vcc, s91, v178
	s_and_b64 s[22:23], s[12:13], exec
	s_nop 0
	v_addc_co_u32_e32 v181, vcc, 0, v179, vcc
	global_load_dwordx4 v[200:203], v[178:179], off
	global_load_dwordx4 v[160:163], v[180:181], off
	s_cselect_b32 s22, 0, 0xfffff000
	s_cselect_b32 s23, 0, -1
	s_cmp_eq_u32 s26, s2
	v_lshl_add_u64 v[120:121], s[14:15], 0, v[182:183]
	s_cselect_b64 s[14:15], -1, 0
	v_lshl_add_u64 v[186:187], v[120:121], 0, s[22:23]
	s_and_b64 s[22:23], s[14:15], exec
	global_load_dwordx4 v[204:207], v[186:187], off
	s_cselect_b32 s72, 0, 0x40000
	v_lshl_add_u64 v[188:189], v[120:121], 0, s[72:73]
	v_lshlrev_b64 v[120:121], 2, v[174:175]
	v_lshl_add_u64 v[184:185], s[36:37], 0, v[120:121]
	global_load_dwordx4 v[220:223], v[188:189], off
	global_load_dwordx4 v[144:147], v[184:185], off
	v_lshl_add_u64 v[122:123], s[46:47], 0, v[120:121]
	v_lshl_add_u64 v[120:121], s[48:49], 0, v[120:121]
	global_load_dwordx4 v[140:143], v[122:123], off
	global_load_dwordx4 v[136:139], v[120:121], off
	global_load_dwordx4 v[132:135], v[184:185], off offset:16
	global_load_dwordx4 v[124:127], v[122:123], off offset:16
	s_nop 0
	global_load_dwordx4 v[120:123], v[120:121], off offset:16
	s_mov_b32 s45, 0x20000
	v_add_co_u32_e32 v190, vcc, s45, v178
	s_mov_b32 s33, 0x30000
	s_nop 0
	v_addc_co_u32_e32 v191, vcc, 0, v179, vcc
	v_or_b32_e32 v152, v211, v219
	v_or_b32_e32 v153, v219, v212
	v_add_co_u32_e32 v192, vcc, s33, v178
	v_lshlrev_b32_e32 v175, 2, v152
	v_lshlrev_b32_e32 v195, 2, v153
	v_addc_co_u32_e32 v193, vcc, 0, v179, vcc
	global_load_dwordx4 v[156:159], v[190:191], off
	global_load_dwordx4 v[152:155], v[192:193], off
	s_add_i32 s50, s0, 0x80
	s_cmpk_lt_i32 s50, 0x2000
	s_cselect_b32 s2, s51, 0x7ff
	s_addk_i32 s0, 0xbf
	s_and_b32 s1, s2, s50
	s_and_b32 s26, s2, s0
	s_cmp_eq_u32 s1, 0
	s_cselect_b64 s[22:23], -1, 0
	s_ashr_i32 s51, s50, 31
	s_lshl_b64 s[0:1], s[50:51], 12
	s_waitcnt vmcnt(0)
	v_mov_b32_dpp v224, v200 row_ror:1 row_mask:0xf bank_mask:0xf
	v_mov_b32_dpp v225, v200 row_ror:15 row_mask:0xf bank_mask:0xf
	v_mov_b32_dpp v228, v202 row_ror:1 row_mask:0xf bank_mask:0xf
	v_mov_b32_dpp v230, v203 row_ror:1 row_mask:0xf bank_mask:0xf
	v_mov_b32_dpp v232, v160 row_ror:15 row_mask:0xf bank_mask:0xf
	v_mov_b32_dpp v226, v201 row_ror:1 row_mask:0xf bank_mask:0xf
	v_mov_b32_dpp v227, v201 row_ror:15 row_mask:0xf bank_mask:0xf
	v_mov_b32_dpp v233, v161 row_ror:15 row_mask:0xf bank_mask:0xf
	v_mov_b32_dpp v229, v202 row_ror:15 row_mask:0xf bank_mask:0xf
	v_cndmask_b32_e64 v204, v204, 0, s[12:13]
	v_cndmask_b32_e64 v207, v207, 0, s[12:13]
	v_cndmask_b32_e64 v206, v206, 0, s[12:13]
	s_waitcnt lgkmcnt(0)
	v_cndmask_b32_e64 v236, v224, v204, s[6:7]
	v_cndmask_b32_e64 v205, v205, 0, s[12:13]
	s_waitcnt lgkmcnt(0)
	v_cndmask_b32_e64 v225, v225, v232, s[8:9]
	v_cndmask_b32_e64 v238, v228, v206, s[6:7]
	v_cndmask_b32_e64 v239, v230, v207, s[6:7]
	v_lshlrev_b32_e32 v206, 16, v236
	v_and_b32_e32 v207, 0xffff0000, v236
	s_waitcnt lgkmcnt(0)
	v_cndmask_b32_e64 v237, v226, v205, s[6:7]
	v_lshlrev_b32_e32 v204, 16, v225
	v_and_b32_e32 v205, 0xffff0000, v225
	v_cndmask_b32_e64 v225, v221, 0, s[14:15]
	v_cndmask_b32_e64 v236, v220, 0, s[14:15]
	v_pk_mul_f32 v[206:207], v[144:145], v[206:207]
	v_lshlrev_b32_e32 v220, 16, v200
	v_and_b32_e32 v221, 0xffff0000, v200
	v_pk_fma_f32 v[206:207], v[140:141], v[220:221], v[206:207]
	v_mov_b32_dpp v234, v162 row_ror:15 row_mask:0xf bank_mask:0xf
	v_pk_fma_f32 v[204:205], v[136:137], v[204:205], v[206:207]
	s_waitcnt lgkmcnt(0)
	v_cndmask_b32_e64 v227, v227, v233, s[8:9]
	v_pk_add_f32 v[204:205], v[204:205], 0 op_sel_hi:[1,0]
	v_lshlrev_b32_e32 v200, 16, v201
	v_pk_mul_f32 v[148:149], v[148:149], v[204:205]
	v_lshlrev_b32_e32 v204, 16, v237
	v_and_b32_e32 v205, 0xffff0000, v237
	v_pk_mul_f32 v[204:205], v[146:147], v[204:205]
	v_and_b32_e32 v201, 0xffff0000, v201
	v_lshlrev_b32_e32 v206, 16, v227
	v_and_b32_e32 v207, 0xffff0000, v227
	v_pk_fma_f32 v[200:201], v[142:143], v[200:201], v[204:205]
	s_waitcnt lgkmcnt(0)
	v_cndmask_b32_e64 v229, v229, v234, s[8:9]
	v_pk_fma_f32 v[200:201], v[138:139], v[206:207], v[200:201]
	v_lshlrev_b32_e32 v206, 16, v202
	v_pk_add_f32 v[200:201], v[200:201], 0 op_sel_hi:[1,0]
	v_and_b32_e32 v207, 0xffff0000, v202
	v_pk_mul_f32 v[150:151], v[150:151], v[200:201]
	v_lshlrev_b32_e32 v200, 16, v238
	v_and_b32_e32 v201, 0xffff0000, v238
	v_pk_mul_f32 v[200:201], v[132:133], v[200:201]
	v_mov_b32_dpp v231, v203 row_ror:15 row_mask:0xf bank_mask:0xf
	v_mov_b32_dpp v235, v163 row_ror:15 row_mask:0xf bank_mask:0xf
	v_lshlrev_b32_e32 v204, 16, v229
	v_and_b32_e32 v205, 0xffff0000, v229
	v_pk_fma_f32 v[200:201], v[124:125], v[206:207], v[200:201]
	v_lshlrev_b32_e32 v202, 16, v203
	v_pk_fma_f32 v[200:201], v[120:121], v[204:205], v[200:201]
	v_and_b32_e32 v203, 0xffff0000, v203
	v_pk_add_f32 v[200:201], v[200:201], 0 op_sel_hi:[1,0]
	s_waitcnt lgkmcnt(0)
	v_cndmask_b32_e64 v231, v231, v235, s[8:9]
	v_pk_mul_f32 v[128:129], v[128:129], v[200:201]
	v_lshlrev_b32_e32 v200, 16, v239
	v_and_b32_e32 v201, 0xffff0000, v239
	v_pk_mul_f32 v[200:201], v[134:135], v[200:201]
	v_lshlrev_b32_e32 v204, 16, v231
	v_pk_fma_f32 v[200:201], v[126:127], v[202:203], v[200:201]
	v_mov_b32_dpp v202, v160 row_ror:1 row_mask:0xf bank_mask:0xf
	v_and_b32_e32 v205, 0xffff0000, v231
	v_pk_fma_f32 v[200:201], v[122:123], v[204:205], v[200:201]
	v_mov_b32_dpp v206, v156 row_ror:15 row_mask:0xf bank_mask:0xf
	v_pk_add_f32 v[200:201], v[200:201], 0 op_sel_hi:[1,0]
	v_cvt_pk_bf16_f32 v148, v148, v149
	v_pk_mul_f32 v[130:131], v[130:131], v[200:201]
	v_cvt_pk_bf16_f32 v149, v150, v151
	v_cvt_pk_bf16_f32 v150, v128, v129
	v_lshl_add_u64 v[128:129], s[34:35], 0, v[208:209]
	v_cvt_pk_bf16_f32 v151, v130, v131
	v_lshl_add_u64 v[128:129], v[128:129], 0, v[182:183]
	v_mov_b32_dpp v203, v161 row_ror:1 row_mask:0xf bank_mask:0xf
	s_waitcnt lgkmcnt(0)
	v_cndmask_b32_e64 v131, v202, v224, s[6:7]
	global_store_dwordx4 v[128:129], v[148:151], off
	v_mov_b32_dpp v207, v157 row_ror:15 row_mask:0xf bank_mask:0xf
	v_lshlrev_b32_e32 v200, 16, v160
	v_lshlrev_b32_e32 v148, 16, v131
	v_and_b32_e32 v149, 0xffff0000, v131
	s_waitcnt lgkmcnt(0)
	v_cndmask_b32_e64 v151, v232, v206, s[8:9]
	v_pk_mul_f32 v[148:149], v[144:145], v[148:149]
	v_and_b32_e32 v201, 0xffff0000, v160
	v_lshlrev_b32_e32 v150, 16, v151
	v_and_b32_e32 v151, 0xffff0000, v151
	v_pk_fma_f32 v[148:149], v[140:141], v[200:201], v[148:149]
	v_mov_b32_dpp v204, v162 row_ror:1 row_mask:0xf bank_mask:0xf
	v_pk_fma_f32 v[148:149], v[136:137], v[150:151], v[148:149]
	s_waitcnt lgkmcnt(0)
	v_cndmask_b32_e64 v220, v203, v226, s[6:7]
	v_pk_add_f32 v[148:149], v[148:149], 0 op_sel_hi:[1,0]
	v_mov_b32_dpp v208, v158 row_ror:15 row_mask:0xf bank_mask:0xf
	v_pk_mul_f32 v[116:117], v[116:117], v[148:149]
	v_lshlrev_b32_e32 v148, 16, v220
	v_and_b32_e32 v149, 0xffff0000, v220
	s_waitcnt lgkmcnt(0)
	v_cndmask_b32_e64 v221, v233, v207, s[8:9]
	v_pk_mul_f32 v[148:149], v[146:147], v[148:149]
	v_lshlrev_b32_e32 v160, 16, v161
	v_and_b32_e32 v161, 0xffff0000, v161
	v_lshlrev_b32_e32 v150, 16, v221
	v_and_b32_e32 v151, 0xffff0000, v221
	v_pk_fma_f32 v[148:149], v[142:143], v[160:161], v[148:149]
	v_mov_b32_dpp v205, v163 row_ror:1 row_mask:0xf bank_mask:0xf
	v_pk_fma_f32 v[148:149], v[138:139], v[150:151], v[148:149]
	s_waitcnt lgkmcnt(0)
	v_cndmask_b32_e64 v224, v204, v228, s[6:7]
	v_pk_add_f32 v[148:149], v[148:149], 0 op_sel_hi:[1,0]
	v_mov_b32_dpp v209, v159 row_ror:15 row_mask:0xf bank_mask:0xf
	v_pk_mul_f32 v[118:119], v[118:119], v[148:149]
	v_lshlrev_b32_e32 v148, 16, v224
	v_and_b32_e32 v149, 0xffff0000, v224
	s_waitcnt lgkmcnt(0)
	v_cndmask_b32_e64 v226, v234, v208, s[8:9]
	v_pk_mul_f32 v[148:149], v[132:133], v[148:149]
	v_lshlrev_b32_e32 v160, 16, v162
	v_and_b32_e32 v161, 0xffff0000, v162
	v_lshlrev_b32_e32 v150, 16, v226
	v_and_b32_e32 v151, 0xffff0000, v226
	v_pk_fma_f32 v[148:149], v[124:125], v[160:161], v[148:149]
	s_waitcnt lgkmcnt(0)
	v_cndmask_b32_e64 v227, v205, v230, s[6:7]
	v_pk_fma_f32 v[148:149], v[120:121], v[150:151], v[148:149]
	s_waitcnt lgkmcnt(0)
	v_cndmask_b32_e64 v228, v235, v209, s[8:9]
	v_pk_add_f32 v[148:149], v[148:149], 0 op_sel_hi:[1,0]
	v_lshlrev_b32_e32 v160, 16, v163
	v_pk_mul_f32 v[112:113], v[112:113], v[148:149]
	v_lshlrev_b32_e32 v148, 16, v227
	v_and_b32_e32 v149, 0xffff0000, v227
	v_pk_mul_f32 v[148:149], v[134:135], v[148:149]
	v_and_b32_e32 v161, 0xffff0000, v163
	v_lshlrev_b32_e32 v150, 16, v228
	v_and_b32_e32 v151, 0xffff0000, v228
	v_pk_fma_f32 v[148:149], v[126:127], v[160:161], v[148:149]
	v_or_b32_e32 v130, 16, v194
	v_pk_fma_f32 v[148:149], v[122:123], v[150:151], v[148:149]
	v_ashrrev_i32_e32 v131, 31, v130
	v_pk_add_f32 v[148:149], v[148:149], 0 op_sel_hi:[1,0]
	v_mov_b32_dpp v160, v152 row_ror:15 row_mask:0xf bank_mask:0xf
	v_pk_mul_f32 v[148:149], v[114:115], v[148:149]
	v_cvt_pk_bf16_f32 v114, v116, v117
	v_cvt_pk_bf16_f32 v117, v148, v149
	v_mov_b32_dpp v148, v156 row_ror:1 row_mask:0xf bank_mask:0xf
	v_cvt_pk_bf16_f32 v116, v112, v113
	v_lshlrev_b64 v[112:113], 12, v[130:131]
	v_lshl_add_u64 v[112:113], s[34:35], 0, v[112:113]
	v_cvt_pk_bf16_f32 v115, v118, v119
	v_lshl_add_u64 v[112:113], v[112:113], 0, v[182:183]
	global_store_dwordx4 v[112:113], v[114:117], off
	v_mov_b32_dpp v149, v157 row_ror:1 row_mask:0xf bank_mask:0xf
	v_mov_b32_dpp v161, v153 row_ror:15 row_mask:0xf bank_mask:0xf
	s_waitcnt lgkmcnt(0)
	v_cndmask_b32_e64 v115, v148, v202, s[6:7]
	v_lshlrev_b32_e32 v116, 16, v115
	v_and_b32_e32 v117, 0xffff0000, v115
	v_cndmask_b32_e64 v119, v206, v160, s[8:9]
	v_pk_mul_f32 v[116:117], v[144:145], v[116:117]
	v_lshlrev_b32_e32 v130, 16, v156
	v_and_b32_e32 v131, 0xffff0000, v156
	v_lshlrev_b32_e32 v118, 16, v119
	v_and_b32_e32 v119, 0xffff0000, v119
	v_pk_fma_f32 v[116:117], v[140:141], v[130:131], v[116:117]
	v_mov_b32_dpp v150, v158 row_ror:1 row_mask:0xf bank_mask:0xf
	v_pk_fma_f32 v[116:117], v[136:137], v[118:119], v[116:117]
	s_waitcnt lgkmcnt(0)
	v_cndmask_b32_e64 v200, v149, v203, s[6:7]
	v_pk_add_f32 v[116:117], v[116:117], 0 op_sel_hi:[1,0]
	v_mov_b32_dpp v162, v154 row_ror:15 row_mask:0xf bank_mask:0xf
	v_pk_mul_f32 v[108:109], v[108:109], v[116:117]
	v_lshlrev_b32_e32 v116, 16, v200
	v_and_b32_e32 v117, 0xffff0000, v200
	s_waitcnt lgkmcnt(0)
	v_cndmask_b32_e64 v201, v207, v161, s[8:9]
	v_pk_mul_f32 v[116:117], v[146:147], v[116:117]
	v_lshlrev_b32_e32 v130, 16, v157
	v_and_b32_e32 v131, 0xffff0000, v157
	v_lshlrev_b32_e32 v118, 16, v201
	v_and_b32_e32 v119, 0xffff0000, v201
	v_pk_fma_f32 v[116:117], v[142:143], v[130:131], v[116:117]
	v_mov_b32_dpp v151, v159 row_ror:1 row_mask:0xf bank_mask:0xf
	v_pk_fma_f32 v[116:117], v[138:139], v[118:119], v[116:117]
	s_waitcnt lgkmcnt(0)
	v_cndmask_b32_e64 v202, v150, v204, s[6:7]
	v_pk_add_f32 v[116:117], v[116:117], 0 op_sel_hi:[1,0]
	v_mov_b32_dpp v163, v155 row_ror:15 row_mask:0xf bank_mask:0xf
	v_pk_mul_f32 v[110:111], v[110:111], v[116:117]
	v_lshlrev_b32_e32 v116, 16, v202
	v_and_b32_e32 v117, 0xffff0000, v202
	s_waitcnt lgkmcnt(0)
	v_cndmask_b32_e64 v203, v208, v162, s[8:9]
	v_pk_mul_f32 v[116:117], v[132:133], v[116:117]
	v_lshlrev_b32_e32 v130, 16, v158
	v_and_b32_e32 v131, 0xffff0000, v158
	v_lshlrev_b32_e32 v118, 16, v203
	v_and_b32_e32 v119, 0xffff0000, v203
	v_pk_fma_f32 v[116:117], v[124:125], v[130:131], v[116:117]
	s_waitcnt lgkmcnt(0)
	v_cndmask_b32_e64 v204, v151, v205, s[6:7]
	v_pk_fma_f32 v[116:117], v[120:121], v[118:119], v[116:117]
	s_waitcnt lgkmcnt(0)
	v_cndmask_b32_e64 v205, v209, v163, s[8:9]
	v_pk_add_f32 v[116:117], v[116:117], 0 op_sel_hi:[1,0]
	v_lshlrev_b32_e32 v130, 16, v159
	v_pk_mul_f32 v[104:105], v[104:105], v[116:117]
	v_lshlrev_b32_e32 v116, 16, v204
	v_and_b32_e32 v117, 0xffff0000, v204
	v_pk_mul_f32 v[116:117], v[134:135], v[116:117]
	v_and_b32_e32 v131, 0xffff0000, v159
	v_lshlrev_b32_e32 v118, 16, v205
	v_and_b32_e32 v119, 0xffff0000, v205
	v_pk_fma_f32 v[116:117], v[126:127], v[130:131], v[116:117]
	v_or_b32_e32 v114, 32, v194
	v_pk_fma_f32 v[116:117], v[122:123], v[118:119], v[116:117]
	v_ashrrev_i32_e32 v115, 31, v114
	v_pk_add_f32 v[116:117], v[116:117], 0 op_sel_hi:[1,0]
	v_cndmask_b32_e64 v222, v222, 0, s[14:15]
	v_pk_mul_f32 v[116:117], v[106:107], v[116:117]
	v_cvt_pk_bf16_f32 v106, v108, v109
	v_cvt_pk_bf16_f32 v108, v104, v105
	v_lshlrev_b64 v[104:105], 12, v[114:115]
	v_lshl_add_u64 v[104:105], s[34:35], 0, v[104:105]
	v_cvt_pk_bf16_f32 v107, v110, v111
	v_cvt_pk_bf16_f32 v109, v116, v117
	v_lshl_add_u64 v[104:105], v[104:105], 0, v[182:183]
	global_store_dwordx4 v[104:105], v[106:109], off
	ds_bpermute_b32 v107, v175, v152
	ds_bpermute_b32 v108, v175, v153
	v_mov_b32_dpp v109, v154 row_ror:1 row_mask:0xf bank_mask:0xf
	v_mov_b32_dpp v110, v155 row_ror:1 row_mask:0xf bank_mask:0xf
	v_cndmask_b32_e64 v111, v160, v236, s[8:9]
	s_waitcnt lgkmcnt(0)
	v_cndmask_b32_e64 v107, v107, v148, s[6:7]
	s_waitcnt lgkmcnt(0)
	v_cndmask_b32_e64 v116, v108, v149, s[6:7]
	s_waitcnt lgkmcnt(0)
	v_cndmask_b32_e64 v118, v109, v150, s[6:7]
	v_lshlrev_b32_e32 v108, 16, v107
	v_and_b32_e32 v109, 0xffff0000, v107
	v_pk_mul_f32 v[108:109], v[144:145], v[108:109]
	v_lshlrev_b32_e32 v114, 16, v152
	v_and_b32_e32 v115, 0xffff0000, v152
	s_waitcnt lgkmcnt(0)
	v_cndmask_b32_e64 v130, v110, v151, s[6:7]
	v_lshlrev_b32_e32 v110, 16, v111
	v_and_b32_e32 v111, 0xffff0000, v111
	v_pk_fma_f32 v[108:109], v[140:141], v[114:115], v[108:109]
	v_cndmask_b32_e64 v117, v161, v225, s[8:9]
	v_pk_fma_f32 v[108:109], v[136:137], v[110:111], v[108:109]
	v_lshlrev_b32_e32 v114, 16, v153
	v_pk_add_f32 v[108:109], v[108:109], 0 op_sel_hi:[1,0]
	v_and_b32_e32 v115, 0xffff0000, v153
	v_pk_mul_f32 v[100:101], v[100:101], v[108:109]
	v_lshlrev_b32_e32 v108, 16, v116
	v_and_b32_e32 v109, 0xffff0000, v116
	v_pk_mul_f32 v[108:109], v[146:147], v[108:109]
	v_lshlrev_b32_e32 v110, 16, v117
	v_and_b32_e32 v111, 0xffff0000, v117
	v_pk_fma_f32 v[108:109], v[142:143], v[114:115], v[108:109]
	v_cndmask_b32_e64 v119, v162, v222, s[8:9]
	v_pk_fma_f32 v[108:109], v[138:139], v[110:111], v[108:109]
	v_lshlrev_b32_e32 v114, 16, v154
	v_pk_add_f32 v[108:109], v[108:109], 0 op_sel_hi:[1,0]
	v_and_b32_e32 v115, 0xffff0000, v154
	v_pk_mul_f32 v[102:103], v[102:103], v[108:109]
	v_lshlrev_b32_e32 v108, 16, v118
	v_and_b32_e32 v109, 0xffff0000, v118
	v_pk_mul_f32 v[108:109], v[132:133], v[108:109]
	v_lshlrev_b32_e32 v110, 16, v119
	v_and_b32_e32 v111, 0xffff0000, v119
	v_pk_fma_f32 v[108:109], v[124:125], v[114:115], v[108:109]
	v_cndmask_b32_e64 v223, v223, 0, s[14:15]
	v_pk_fma_f32 v[108:109], v[120:121], v[110:111], v[108:109]
	v_cndmask_b32_e64 v131, v163, v223, s[8:9]
	v_pk_add_f32 v[108:109], v[108:109], 0 op_sel_hi:[1,0]
	v_lshlrev_b32_e32 v114, 16, v155
	v_pk_mul_f32 v[108:109], v[96:97], v[108:109]
	v_lshlrev_b32_e32 v96, 16, v130
	v_and_b32_e32 v97, 0xffff0000, v130
	v_pk_mul_f32 v[96:97], v[134:135], v[96:97]
	v_and_b32_e32 v115, 0xffff0000, v155
	v_lshlrev_b32_e32 v110, 16, v131
	v_and_b32_e32 v111, 0xffff0000, v131
	v_pk_fma_f32 v[96:97], v[126:127], v[114:115], v[96:97]
	v_or_b32_e32 v106, 48, v194
	v_pk_fma_f32 v[96:97], v[122:123], v[110:111], v[96:97]
	v_or_b32_e32 v152, s50, v196
	s_add_u32 s50, s30, s0
	v_pk_add_f32 v[96:97], v[96:97], 0 op_sel_hi:[1,0]
	v_ashrrev_i32_e32 v107, 31, v106
	s_addc_u32 s51, s31, s1
	v_pk_mul_f32 v[110:111], v[98:99], v[96:97]
	v_cvt_pk_bf16_f32 v96, v100, v101
	v_lshlrev_b64 v[100:101], 12, v[106:107]
	s_and_b64 s[0:1], s[22:23], exec
	v_lshl_add_u64 v[100:101], s[34:35], 0, v[100:101]
	s_cselect_b32 s58, 0, 0xfffff000
	s_cselect_b32 s59, 0, -1
	s_cmp_eq_u32 s26, s2
	v_cvt_pk_bf16_f32 v97, v102, v103
	v_cvt_pk_bf16_f32 v98, v108, v109
	v_cvt_pk_bf16_f32 v99, v110, v111
	v_lshl_add_u64 v[106:107], v[100:101], 0, v[182:183]
	s_cselect_b64 s[0:1], -1, 0
	global_store_dwordx4 v[106:107], v[96:99], off
	v_ashrrev_i32_e32 v153, 31, v152
	v_lshlrev_b64 v[162:163], 12, v[152:153]
	v_lshl_add_u64 v[96:97], s[50:51], 0, v[182:183]
	s_and_b64 s[50:51], s[0:1], exec
	s_cselect_b32 s72, 0, 0x40000
	v_lshl_add_u64 v[108:109], v[96:97], 0, s[58:59]
	v_lshl_add_u64 v[110:111], v[96:97], 0, s[72:73]
	v_lshl_add_u64 v[96:97], s[30:31], 0, v[162:163]
	v_lshl_add_u64 v[114:115], v[96:97], 0, v[182:183]
	v_add_co_u32_e32 v116, vcc, s91, v114
	global_load_dwordx4 v[158:161], v[114:115], off
	s_nop 0
	v_addc_co_u32_e32 v117, vcc, 0, v115, vcc
	global_load_dwordx4 v[148:151], v[108:109], off
	global_load_dwordx4 v[154:157], v[110:111], off
	global_load_dwordx4 v[200:203], v[116:117], off
	v_add_co_u32_e32 v118, vcc, s45, v114
	s_waitcnt vmcnt(3)
	v_mov_b32_dpp v204, v158 row_ror:1 row_mask:0xf bank_mask:0xf
	v_addc_co_u32_e32 v119, vcc, 0, v115, vcc
	v_add_co_u32_e32 v130, vcc, s33, v114
	s_waitcnt vmcnt(1)
	v_cndmask_b32_e64 v194, v154, 0, s[0:1]
	v_addc_co_u32_e32 v131, vcc, 0, v115, vcc
	global_load_dwordx4 v[100:103], v[118:119], off
	global_load_dwordx4 v[96:99], v[130:131], off
	v_mov_b32_dpp v154, v158 row_ror:15 row_mask:0xf bank_mask:0xf
	v_mov_b32_dpp v205, v159 row_ror:1 row_mask:0xf bank_mask:0xf
	s_waitcnt vmcnt(2)
	v_mov_b32_dpp v220, v200 row_ror:15 row_mask:0xf bank_mask:0xf
	v_cndmask_b32_e64 v153, v157, 0, s[0:1]
	v_cndmask_b32_e64 v157, v155, 0, s[0:1]
	v_mov_b32_dpp v155, v159 row_ror:15 row_mask:0xf bank_mask:0xf
	v_mov_b32_dpp v206, v160 row_ror:1 row_mask:0xf bank_mask:0xf
	v_mov_b32_dpp v208, v161 row_ror:1 row_mask:0xf bank_mask:0xf
	v_mov_b32_dpp v221, v201 row_ror:15 row_mask:0xf bank_mask:0xf
	v_cndmask_b32_e64 v148, v148, 0, s[22:23]
	v_cndmask_b32_e64 v149, v149, 0, s[22:23]
	s_waitcnt lgkmcnt(0)
	v_cndmask_b32_e64 v224, v204, v148, s[6:7]
	v_cndmask_b32_e64 v151, v151, 0, s[22:23]
	v_cndmask_b32_e64 v150, v150, 0, s[22:23]
	s_waitcnt lgkmcnt(0)
	v_cndmask_b32_e64 v154, v154, v220, s[8:9]
	v_cndmask_b32_e64 v225, v205, v149, s[6:7]
	v_lshlrev_b32_e32 v148, 16, v224
	v_and_b32_e32 v149, 0xffff0000, v224
	s_waitcnt lgkmcnt(0)
	v_cndmask_b32_e64 v226, v155, v221, s[8:9]
	v_cndmask_b32_e64 v227, v206, v150, s[6:7]
	v_cndmask_b32_e64 v228, v208, v151, s[6:7]
	v_lshlrev_b32_e32 v150, 16, v154
	v_and_b32_e32 v151, 0xffff0000, v154
	v_pk_mul_f32 v[148:149], v[144:145], v[148:149]
	v_lshlrev_b32_e32 v154, 16, v158
	v_and_b32_e32 v155, 0xffff0000, v158
	v_pk_fma_f32 v[148:149], v[140:141], v[154:155], v[148:149]
	v_mov_b32_dpp v207, v160 row_ror:15 row_mask:0xf bank_mask:0xf
	v_pk_fma_f32 v[148:149], v[136:137], v[150:151], v[148:149]
	v_mov_b32_dpp v222, v202 row_ror:15 row_mask:0xf bank_mask:0xf
	v_pk_add_f32 v[148:149], v[148:149], 0 op_sel_hi:[1,0]
	v_lshlrev_b32_e32 v154, 16, v159
	v_pk_mul_f32 v[92:93], v[92:93], v[148:149]
	v_lshlrev_b32_e32 v148, 16, v225
	v_and_b32_e32 v149, 0xffff0000, v225
	v_pk_mul_f32 v[148:149], v[146:147], v[148:149]
	v_and_b32_e32 v155, 0xffff0000, v159
	v_lshlrev_b32_e32 v150, 16, v226
	v_and_b32_e32 v151, 0xffff0000, v226
	v_pk_fma_f32 v[148:149], v[142:143], v[154:155], v[148:149]
	v_mov_b32_dpp v209, v161 row_ror:15 row_mask:0xf bank_mask:0xf
	v_pk_fma_f32 v[148:149], v[138:139], v[150:151], v[148:149]
	v_mov_b32_dpp v223, v203 row_ror:15 row_mask:0xf bank_mask:0xf
	v_pk_add_f32 v[148:149], v[148:149], 0 op_sel_hi:[1,0]
	s_waitcnt lgkmcnt(0)
	v_cndmask_b32_e64 v207, v207, v222, s[8:9]
	v_pk_mul_f32 v[94:95], v[94:95], v[148:149]
	v_lshlrev_b32_e32 v148, 16, v227
	v_and_b32_e32 v149, 0xffff0000, v227
	v_pk_mul_f32 v[148:149], v[132:133], v[148:149]
	v_lshlrev_b32_e32 v154, 16, v160
	v_and_b32_e32 v155, 0xffff0000, v160
	v_lshlrev_b32_e32 v150, 16, v207
	v_and_b32_e32 v151, 0xffff0000, v207
	v_pk_fma_f32 v[148:149], v[124:125], v[154:155], v[148:149]
	s_waitcnt lgkmcnt(0)
	v_cndmask_b32_e64 v209, v209, v223, s[8:9]
	v_pk_fma_f32 v[148:149], v[120:121], v[150:151], v[148:149]
	v_lshlrev_b32_e32 v154, 16, v161
	v_pk_add_f32 v[148:149], v[148:149], 0 op_sel_hi:[1,0]
	v_and_b32_e32 v155, 0xffff0000, v161
	v_pk_mul_f32 v[148:149], v[88:89], v[148:149]
	v_lshlrev_b32_e32 v88, 16, v228
	v_and_b32_e32 v89, 0xffff0000, v228
	v_pk_mul_f32 v[88:89], v[134:135], v[88:89]
	v_lshlrev_b32_e32 v150, 16, v209
	v_and_b32_e32 v151, 0xffff0000, v209
	v_pk_fma_f32 v[88:89], v[126:127], v[154:155], v[88:89]
	v_mov_b32_dpp v154, v200 row_ror:1 row_mask:0xf bank_mask:0xf
	v_pk_fma_f32 v[88:89], v[122:123], v[150:151], v[88:89]
	v_mov_b32_dpp v155, v201 row_ror:1 row_mask:0xf bank_mask:0xf
	v_pk_add_f32 v[88:89], v[88:89], 0 op_sel_hi:[1,0]
	v_mov_b32_dpp v158, v202 row_ror:1 row_mask:0xf bank_mask:0xf
	v_pk_mul_f32 v[150:151], v[90:91], v[88:89]
	v_cvt_pk_bf16_f32 v88, v92, v93
	v_lshl_add_u64 v[92:93], s[34:35], 0, v[162:163]
	v_cvt_pk_bf16_f32 v89, v94, v95
	v_cvt_pk_bf16_f32 v90, v148, v149
	v_cvt_pk_bf16_f32 v91, v150, v151
	s_waitcnt vmcnt(1)
	v_mov_b32_dpp v160, v100 row_ror:15 row_mask:0xf bank_mask:0xf
	v_lshl_add_u64 v[148:149], v[92:93], 0, v[182:183]
	global_store_dwordx4 v[148:149], v[88:91], off
	v_mov_b32_dpp v161, v101 row_ror:15 row_mask:0xf bank_mask:0xf
	v_lshlrev_b32_e32 v94, 16, v200
	s_waitcnt lgkmcnt(0)
	v_cndmask_b32_e64 v89, v154, v204, s[6:7]
	v_lshlrev_b32_e32 v90, 16, v89
	v_and_b32_e32 v91, 0xffff0000, v89
	s_waitcnt lgkmcnt(0)
	v_cndmask_b32_e64 v93, v220, v160, s[8:9]
	v_pk_mul_f32 v[90:91], v[144:145], v[90:91]
	v_and_b32_e32 v95, 0xffff0000, v200
	v_lshlrev_b32_e32 v92, 16, v93
	v_and_b32_e32 v93, 0xffff0000, v93
	v_pk_fma_f32 v[90:91], v[140:141], v[94:95], v[90:91]
	v_cndmask_b32_e64 v150, v155, v205, s[6:7]
	v_pk_fma_f32 v[90:91], v[136:137], v[92:93], v[90:91]
	v_mov_b32_dpp v162, v102 row_ror:15 row_mask:0xf bank_mask:0xf
	v_pk_add_f32 v[90:91], v[90:91], 0 op_sel_hi:[1,0]
	s_waitcnt lgkmcnt(0)
	v_cndmask_b32_e64 v151, v221, v161, s[8:9]
	v_pk_mul_f32 v[84:85], v[84:85], v[90:91]
	v_lshlrev_b32_e32 v90, 16, v150
	v_and_b32_e32 v91, 0xffff0000, v150
	v_pk_mul_f32 v[90:91], v[146:147], v[90:91]
	v_lshlrev_b32_e32 v94, 16, v201
	v_and_b32_e32 v95, 0xffff0000, v201
	v_lshlrev_b32_e32 v92, 16, v151
	v_and_b32_e32 v93, 0xffff0000, v151
	v_pk_fma_f32 v[90:91], v[142:143], v[94:95], v[90:91]
	v_mov_b32_dpp v159, v203 row_ror:1 row_mask:0xf bank_mask:0xf
	v_pk_fma_f32 v[90:91], v[138:139], v[92:93], v[90:91]
	v_cndmask_b32_e64 v204, v158, v206, s[6:7]
	v_pk_add_f32 v[90:91], v[90:91], 0 op_sel_hi:[1,0]
	v_mov_b32_dpp v163, v103 row_ror:15 row_mask:0xf bank_mask:0xf
	v_pk_mul_f32 v[86:87], v[86:87], v[90:91]
	v_lshlrev_b32_e32 v90, 16, v204
	v_and_b32_e32 v91, 0xffff0000, v204
	s_waitcnt lgkmcnt(0)
	v_cndmask_b32_e64 v205, v222, v162, s[8:9]
	v_pk_mul_f32 v[90:91], v[132:133], v[90:91]
	v_lshlrev_b32_e32 v94, 16, v202
	v_and_b32_e32 v95, 0xffff0000, v202
	v_lshlrev_b32_e32 v92, 16, v205
	v_and_b32_e32 v93, 0xffff0000, v205
	v_pk_fma_f32 v[90:91], v[124:125], v[94:95], v[90:91]
	s_waitcnt lgkmcnt(0)
	v_cndmask_b32_e64 v206, v159, v208, s[6:7]
	v_pk_fma_f32 v[90:91], v[120:121], v[92:93], v[90:91]
	s_waitcnt lgkmcnt(0)
	v_cndmask_b32_e64 v207, v223, v163, s[8:9]
	v_pk_add_f32 v[90:91], v[90:91], 0 op_sel_hi:[1,0]
	v_lshlrev_b32_e32 v94, 16, v203
	v_pk_mul_f32 v[90:91], v[80:81], v[90:91]
	v_lshlrev_b32_e32 v80, 16, v206
	v_and_b32_e32 v81, 0xffff0000, v206
	v_pk_mul_f32 v[80:81], v[134:135], v[80:81]
	v_and_b32_e32 v95, 0xffff0000, v203
	v_lshlrev_b32_e32 v92, 16, v207
	v_and_b32_e32 v93, 0xffff0000, v207
	v_pk_fma_f32 v[80:81], v[126:127], v[94:95], v[80:81]
	v_or_b32_e32 v88, 16, v152
	v_pk_fma_f32 v[80:81], v[122:123], v[92:93], v[80:81]
	v_ashrrev_i32_e32 v89, 31, v88
	v_pk_add_f32 v[80:81], v[80:81], 0 op_sel_hi:[1,0]
	s_waitcnt vmcnt(1)
	v_mov_b32_dpp v94, v98 row_ror:15 row_mask:0xf bank_mask:0xf
	v_pk_mul_f32 v[92:93], v[82:83], v[80:81]
	v_cvt_pk_bf16_f32 v80, v84, v85
	v_lshlrev_b64 v[84:85], 12, v[88:89]
	v_mov_b32_dpp v88, v100 row_ror:1 row_mask:0xf bank_mask:0xf
	v_cvt_pk_bf16_f32 v83, v92, v93
	v_mov_b32_dpp v92, v96 row_ror:15 row_mask:0xf bank_mask:0xf
	v_lshl_add_u64 v[84:85], s[34:35], 0, v[84:85]
	v_cvt_pk_bf16_f32 v81, v86, v87
	v_cvt_pk_bf16_f32 v82, v90, v91
	v_lshl_add_u64 v[150:151], v[84:85], 0, v[182:183]
	global_store_dwordx4 v[150:151], v[80:83], off
	v_mov_b32_dpp v89, v101 row_ror:1 row_mask:0xf bank_mask:0xf
	v_mov_b32_dpp v93, v97 row_ror:15 row_mask:0xf bank_mask:0xf
	s_waitcnt lgkmcnt(0)
	v_cndmask_b32_e64 v81, v88, v154, s[6:7]
	v_lshlrev_b32_e32 v82, 16, v81
	v_and_b32_e32 v83, 0xffff0000, v81
	s_waitcnt lgkmcnt(0)
	v_cndmask_b32_e64 v85, v160, v92, s[8:9]
	v_pk_mul_f32 v[82:83], v[144:145], v[82:83]
	v_lshlrev_b32_e32 v86, 16, v100
	v_and_b32_e32 v87, 0xffff0000, v100
	v_lshlrev_b32_e32 v84, 16, v85
	v_and_b32_e32 v85, 0xffff0000, v85
	v_pk_fma_f32 v[82:83], v[140:141], v[86:87], v[82:83]
	v_mov_b32_dpp v90, v102 row_ror:1 row_mask:0xf bank_mask:0xf
	v_pk_fma_f32 v[82:83], v[136:137], v[84:85], v[82:83]
	s_waitcnt lgkmcnt(0)
	v_cndmask_b32_e64 v154, v89, v155, s[6:7]
	v_pk_add_f32 v[82:83], v[82:83], 0 op_sel_hi:[1,0]
	s_waitcnt lgkmcnt(0)
	v_cndmask_b32_e64 v155, v161, v93, s[8:9]
	v_pk_mul_f32 v[76:77], v[76:77], v[82:83]
	v_lshlrev_b32_e32 v82, 16, v154
	v_and_b32_e32 v83, 0xffff0000, v154
	v_pk_mul_f32 v[82:83], v[146:147], v[82:83]
	v_lshlrev_b32_e32 v86, 16, v101
	v_and_b32_e32 v87, 0xffff0000, v101
	v_lshlrev_b32_e32 v84, 16, v155
	v_and_b32_e32 v85, 0xffff0000, v155
	v_pk_fma_f32 v[82:83], v[142:143], v[86:87], v[82:83]
	v_mov_b32_dpp v91, v103 row_ror:1 row_mask:0xf bank_mask:0xf
	v_pk_fma_f32 v[82:83], v[138:139], v[84:85], v[82:83]
	s_waitcnt lgkmcnt(0)
	v_cndmask_b32_e64 v158, v90, v158, s[6:7]
	v_pk_add_f32 v[82:83], v[82:83], 0 op_sel_hi:[1,0]
	v_mov_b32_dpp v95, v99 row_ror:15 row_mask:0xf bank_mask:0xf
	v_pk_mul_f32 v[78:79], v[78:79], v[82:83]
	v_lshlrev_b32_e32 v82, 16, v158
	v_and_b32_e32 v83, 0xffff0000, v158
	v_cndmask_b32_e64 v160, v162, v94, s[8:9]
	v_pk_mul_f32 v[82:83], v[132:133], v[82:83]
	v_lshlrev_b32_e32 v86, 16, v102
	v_and_b32_e32 v87, 0xffff0000, v102
	v_lshlrev_b32_e32 v84, 16, v160
	v_and_b32_e32 v85, 0xffff0000, v160
	v_pk_fma_f32 v[82:83], v[124:125], v[86:87], v[82:83]
	s_waitcnt lgkmcnt(0)
	v_cndmask_b32_e64 v159, v91, v159, s[6:7]
	v_pk_fma_f32 v[82:83], v[120:121], v[84:85], v[82:83]
	s_waitcnt lgkmcnt(0)
	v_cndmask_b32_e64 v161, v163, v95, s[8:9]
	v_pk_add_f32 v[82:83], v[82:83], 0 op_sel_hi:[1,0]
	v_lshlrev_b32_e32 v86, 16, v103
	v_pk_mul_f32 v[82:83], v[72:73], v[82:83]
	v_lshlrev_b32_e32 v72, 16, v159
	v_and_b32_e32 v73, 0xffff0000, v159
	v_pk_mul_f32 v[72:73], v[134:135], v[72:73]
	v_and_b32_e32 v87, 0xffff0000, v103
	v_lshlrev_b32_e32 v84, 16, v161
	v_and_b32_e32 v85, 0xffff0000, v161
	v_pk_fma_f32 v[72:73], v[126:127], v[86:87], v[72:73]
	v_or_b32_e32 v80, 32, v152
	v_pk_fma_f32 v[72:73], v[122:123], v[84:85], v[72:73]
	v_ashrrev_i32_e32 v81, 31, v80
	v_pk_add_f32 v[72:73], v[72:73], 0 op_sel_hi:[1,0]
	v_cndmask_b32_e64 v156, v156, 0, s[0:1]
	v_pk_mul_f32 v[84:85], v[74:75], v[72:73]
	v_cvt_pk_bf16_f32 v72, v76, v77
	v_lshlrev_b64 v[76:77], 12, v[80:81]
	v_lshl_add_u64 v[76:77], s[34:35], 0, v[76:77]
	v_cvt_pk_bf16_f32 v73, v78, v79
	v_cvt_pk_bf16_f32 v74, v82, v83
	v_cvt_pk_bf16_f32 v75, v84, v85
	v_lshl_add_u64 v[100:101], v[76:77], 0, v[182:183]
	global_store_dwordx4 v[100:101], v[72:75], off
	ds_bpermute_b32 v73, v175, v96
	ds_bpermute_b32 v74, v175, v97
	v_mov_b32_dpp v75, v98 row_ror:1 row_mask:0xf bank_mask:0xf
	v_mov_b32_dpp v76, v99 row_ror:1 row_mask:0xf bank_mask:0xf
	v_cndmask_b32_e64 v77, v92, v194, s[8:9]
	s_waitcnt lgkmcnt(0)
	v_cndmask_b32_e64 v73, v73, v88, s[6:7]
	s_waitcnt lgkmcnt(0)
	v_cndmask_b32_e64 v80, v74, v89, s[6:7]
	s_waitcnt lgkmcnt(0)
	v_cndmask_b32_e64 v82, v75, v90, s[6:7]
	v_lshlrev_b32_e32 v74, 16, v73
	v_and_b32_e32 v75, 0xffff0000, v73
	v_pk_mul_f32 v[74:75], v[144:145], v[74:75]
	v_lshlrev_b32_e32 v78, 16, v96
	v_and_b32_e32 v79, 0xffff0000, v96
	s_waitcnt lgkmcnt(0)
	v_cndmask_b32_e64 v84, v76, v91, s[6:7]
	v_lshlrev_b32_e32 v76, 16, v77
	v_and_b32_e32 v77, 0xffff0000, v77
	v_pk_fma_f32 v[74:75], v[140:141], v[78:79], v[74:75]
	v_cndmask_b32_e64 v81, v93, v157, s[8:9]
	v_pk_fma_f32 v[74:75], v[136:137], v[76:77], v[74:75]
	v_lshlrev_b32_e32 v78, 16, v97
	v_pk_add_f32 v[74:75], v[74:75], 0 op_sel_hi:[1,0]
	v_and_b32_e32 v79, 0xffff0000, v97
	v_pk_mul_f32 v[68:69], v[68:69], v[74:75]
	v_lshlrev_b32_e32 v74, 16, v80
	v_and_b32_e32 v75, 0xffff0000, v80
	v_pk_mul_f32 v[74:75], v[146:147], v[74:75]
	v_lshlrev_b32_e32 v76, 16, v81
	v_and_b32_e32 v77, 0xffff0000, v81
	v_pk_fma_f32 v[74:75], v[142:143], v[78:79], v[74:75]
	v_cndmask_b32_e64 v83, v94, v156, s[8:9]
	v_pk_fma_f32 v[74:75], v[138:139], v[76:77], v[74:75]
	v_lshlrev_b32_e32 v78, 16, v98
	v_pk_add_f32 v[74:75], v[74:75], 0 op_sel_hi:[1,0]
	v_and_b32_e32 v79, 0xffff0000, v98
	v_pk_mul_f32 v[70:71], v[70:71], v[74:75]
	v_lshlrev_b32_e32 v74, 16, v82
	v_and_b32_e32 v75, 0xffff0000, v82
	v_pk_mul_f32 v[74:75], v[132:133], v[74:75]
	v_lshlrev_b32_e32 v76, 16, v83
	v_and_b32_e32 v77, 0xffff0000, v83
	v_pk_fma_f32 v[74:75], v[124:125], v[78:79], v[74:75]
	v_cndmask_b32_e64 v85, v95, v153, s[8:9]
	v_pk_fma_f32 v[74:75], v[120:121], v[76:77], v[74:75]
	v_lshlrev_b32_e32 v78, 16, v99
	v_pk_add_f32 v[74:75], v[74:75], 0 op_sel_hi:[1,0]
	v_and_b32_e32 v79, 0xffff0000, v99
	v_pk_mul_f32 v[74:75], v[64:65], v[74:75]
	v_lshlrev_b32_e32 v64, 16, v84
	v_and_b32_e32 v65, 0xffff0000, v84
	v_pk_mul_f32 v[64:65], v[134:135], v[64:65]
	v_lshlrev_b32_e32 v76, 16, v85
	v_and_b32_e32 v77, 0xffff0000, v85
	v_pk_fma_f32 v[64:65], v[126:127], v[78:79], v[64:65]
	v_or_b32_e32 v72, 48, v152
	v_pk_fma_f32 v[64:65], v[122:123], v[76:77], v[64:65]
	v_ashrrev_i32_e32 v73, 31, v72
	v_pk_add_f32 v[64:65], v[64:65], 0 op_sel_hi:[1,0]
	s_andn2_b64 vcc, exec, s[56:57]
	v_pk_mul_f32 v[76:77], v[66:67], v[64:65]
	v_cvt_pk_bf16_f32 v64, v68, v69
	v_lshlrev_b64 v[68:69], 12, v[72:73]
	v_lshl_add_u64 v[68:69], s[34:35], 0, v[68:69]
	v_cvt_pk_bf16_f32 v65, v70, v71
	v_cvt_pk_bf16_f32 v66, v74, v75
	v_cvt_pk_bf16_f32 v67, v76, v77
	v_lshl_add_u64 v[96:97], v[68:69], 0, v[182:183]
	global_store_dwordx4 v[96:97], v[64:67], off
	global_load_dwordx4 v[120:123], v[186:187], off offset:256
	global_load_dwordx4 v[124:127], v[188:189], off offset:256
	global_load_dwordx4 v[132:135], v[178:179], off offset:256
	global_load_dwordx4 v[136:139], v[180:181], off offset:256
	global_load_dwordx4 v[84:87], v[184:185], off offset:512
	v_or_b32_e32 v64, 0x80, v174
	v_ashrrev_i32_e32 v65, 31, v64
	v_lshlrev_b64 v[64:65], 2, v[64:65]
	v_lshl_add_u64 v[66:67], s[46:47], 0, v[64:65]
	v_lshl_add_u64 v[64:65], s[48:49], 0, v[64:65]
	global_load_dwordx4 v[80:83], v[66:67], off
	global_load_dwordx4 v[76:79], v[64:65], off
	global_load_dwordx4 v[72:75], v[184:185], off offset:528
	global_load_dwordx4 v[68:71], v[66:67], off offset:16
	s_nop 0
	global_load_dwordx4 v[64:67], v[64:65], off offset:16
	s_nop 0
	global_load_dwordx4 v[92:95], v[190:191], off offset:256
	global_load_dwordx4 v[88:91], v[192:193], off offset:256
	s_waitcnt vmcnt(11)
	v_cndmask_b32_e64 v98, v123, 0, s[12:13]
	s_waitcnt vmcnt(10)
	v_cndmask_b32_e64 v123, v126, 0, s[14:15]
	s_waitcnt vmcnt(9)
	v_mov_b32_dpp v126, v132 row_ror:1 row_mask:0xf bank_mask:0xf
	v_cndmask_b32_e64 v103, v120, 0, s[12:13]
	v_mov_b32_dpp v120, v132 row_ror:15 row_mask:0xf bank_mask:0xf
	v_mov_b32_dpp v140, v134 row_ror:1 row_mask:0xf bank_mask:0xf
	v_mov_b32_dpp v142, v135 row_ror:1 row_mask:0xf bank_mask:0xf
	s_waitcnt vmcnt(8)
	v_mov_b32_dpp v144, v136 row_ror:15 row_mask:0xf bank_mask:0xf
	v_cndmask_b32_e64 v99, v122, 0, s[12:13]
	v_cndmask_b32_e64 v102, v121, 0, s[12:13]
	v_cndmask_b32_e64 v122, v127, 0, s[14:15]
	v_mov_b32_dpp v127, v133 row_ror:1 row_mask:0xf bank_mask:0xf
	v_mov_b32_dpp v121, v133 row_ror:15 row_mask:0xf bank_mask:0xf
	v_mov_b32_dpp v145, v137 row_ror:15 row_mask:0xf bank_mask:0xf
	s_waitcnt lgkmcnt(0)
	v_cndmask_b32_e64 v103, v126, v103, s[6:7]
	s_waitcnt lgkmcnt(0)
	v_cndmask_b32_e64 v120, v120, v144, s[8:9]
	v_cndmask_b32_e64 v154, v140, v99, s[6:7]
	v_cndmask_b32_e64 v155, v142, v98, s[6:7]
	v_lshlrev_b32_e32 v98, 16, v103
	v_and_b32_e32 v99, 0xffff0000, v103
	s_waitcnt lgkmcnt(0)
	v_cndmask_b32_e64 v152, v127, v102, s[6:7]
	s_waitcnt lgkmcnt(0)
	v_cndmask_b32_e64 v153, v121, v145, s[8:9]
	v_lshlrev_b32_e32 v102, 16, v120
	v_and_b32_e32 v103, 0xffff0000, v120
	s_waitcnt vmcnt(7)
	v_pk_mul_f32 v[98:99], v[84:85], v[98:99]
	v_lshlrev_b32_e32 v120, 16, v132
	v_and_b32_e32 v121, 0xffff0000, v132
	s_waitcnt vmcnt(6)
	v_pk_fma_f32 v[98:99], v[80:81], v[120:121], v[98:99]
	v_mov_b32_dpp v141, v134 row_ror:15 row_mask:0xf bank_mask:0xf
	s_waitcnt vmcnt(5)
	v_pk_fma_f32 v[98:99], v[76:77], v[102:103], v[98:99]
	v_mov_b32_dpp v146, v138 row_ror:15 row_mask:0xf bank_mask:0xf
	v_pk_add_f32 v[98:99], v[98:99], 0 op_sel_hi:[1,0]
	v_lshlrev_b32_e32 v120, 16, v133
	v_pk_mul_f32 v[60:61], v[60:61], v[98:99]
	v_lshlrev_b32_e32 v98, 16, v152
	v_and_b32_e32 v99, 0xffff0000, v152
	v_pk_mul_f32 v[98:99], v[86:87], v[98:99]
	v_and_b32_e32 v121, 0xffff0000, v133
	v_lshlrev_b32_e32 v102, 16, v153
	v_and_b32_e32 v103, 0xffff0000, v153
	v_pk_fma_f32 v[98:99], v[82:83], v[120:121], v[98:99]
	v_mov_b32_dpp v143, v135 row_ror:15 row_mask:0xf bank_mask:0xf
	v_pk_fma_f32 v[98:99], v[78:79], v[102:103], v[98:99]
	v_mov_b32_dpp v147, v139 row_ror:15 row_mask:0xf bank_mask:0xf
	v_pk_add_f32 v[98:99], v[98:99], 0 op_sel_hi:[1,0]
	s_waitcnt lgkmcnt(0)
	v_cndmask_b32_e64 v141, v141, v146, s[8:9]
	v_pk_mul_f32 v[62:63], v[62:63], v[98:99]
	v_lshlrev_b32_e32 v98, 16, v154
	v_and_b32_e32 v99, 0xffff0000, v154
	s_waitcnt vmcnt(4)
	v_pk_mul_f32 v[98:99], v[72:73], v[98:99]
	v_lshlrev_b32_e32 v120, 16, v134
	v_and_b32_e32 v121, 0xffff0000, v134
	v_lshlrev_b32_e32 v102, 16, v141
	v_and_b32_e32 v103, 0xffff0000, v141
	s_waitcnt vmcnt(3)
	v_pk_fma_f32 v[98:99], v[68:69], v[120:121], v[98:99]
	s_waitcnt lgkmcnt(0)
	v_cndmask_b32_e64 v143, v143, v147, s[8:9]
	s_waitcnt vmcnt(2)
	v_pk_fma_f32 v[98:99], v[64:65], v[102:103], v[98:99]
	v_lshlrev_b32_e32 v120, 16, v135
	v_pk_add_f32 v[98:99], v[98:99], 0 op_sel_hi:[1,0]
	v_and_b32_e32 v121, 0xffff0000, v135
	v_pk_mul_f32 v[98:99], v[56:57], v[98:99]
	v_lshlrev_b32_e32 v56, 16, v155
	v_and_b32_e32 v57, 0xffff0000, v155
	v_pk_mul_f32 v[56:57], v[74:75], v[56:57]
	v_lshlrev_b32_e32 v102, 16, v143
	v_and_b32_e32 v103, 0xffff0000, v143
	v_pk_fma_f32 v[56:57], v[70:71], v[120:121], v[56:57]
	s_waitcnt vmcnt(1)
	v_mov_b32_dpp v120, v94 row_ror:15 row_mask:0xf bank_mask:0xf
	v_pk_fma_f32 v[56:57], v[66:67], v[102:103], v[56:57]
	v_mov_b32_dpp v121, v95 row_ror:15 row_mask:0xf bank_mask:0xf
	v_pk_add_f32 v[56:57], v[56:57], 0 op_sel_hi:[1,0]
	v_cndmask_b32_e64 v124, v124, 0, s[14:15]
	v_pk_mul_f32 v[102:103], v[58:59], v[56:57]
	v_cvt_pk_bf16_f32 v57, v62, v63
	v_mov_b32_dpp v62, v136 row_ror:1 row_mask:0xf bank_mask:0xf
	v_cvt_pk_bf16_f32 v59, v102, v103
	v_mov_b32_dpp v102, v92 row_ror:15 row_mask:0xf bank_mask:0xf
	v_cvt_pk_bf16_f32 v56, v60, v61
	v_cvt_pk_bf16_f32 v58, v98, v99
	global_store_dwordx4 v[128:129], v[56:59], off offset:256
	v_mov_b32_dpp v63, v137 row_ror:1 row_mask:0xf bank_mask:0xf
	v_mov_b32_dpp v103, v93 row_ror:15 row_mask:0xf bank_mask:0xf
	s_waitcnt lgkmcnt(0)
	v_cndmask_b32_e64 v57, v62, v126, s[6:7]
	v_lshlrev_b32_e32 v56, 16, v57
	v_and_b32_e32 v57, 0xffff0000, v57
	s_waitcnt lgkmcnt(0)
	v_cndmask_b32_e64 v59, v144, v102, s[8:9]
	v_pk_mul_f32 v[56:57], v[84:85], v[56:57]
	v_lshlrev_b32_e32 v60, 16, v136
	v_and_b32_e32 v61, 0xffff0000, v136
	v_lshlrev_b32_e32 v58, 16, v59
	v_and_b32_e32 v59, 0xffff0000, v59
	v_pk_fma_f32 v[56:57], v[80:81], v[60:61], v[56:57]
	v_mov_b32_dpp v98, v138 row_ror:1 row_mask:0xf bank_mask:0xf
	v_pk_fma_f32 v[56:57], v[76:77], v[58:59], v[56:57]
	s_waitcnt lgkmcnt(0)
	v_cndmask_b32_e64 v126, v63, v127, s[6:7]
	v_pk_add_f32 v[56:57], v[56:57], 0 op_sel_hi:[1,0]
	s_waitcnt lgkmcnt(0)
	v_cndmask_b32_e64 v127, v145, v103, s[8:9]
	v_pk_mul_f32 v[52:53], v[52:53], v[56:57]
	v_lshlrev_b32_e32 v56, 16, v126
	v_and_b32_e32 v57, 0xffff0000, v126
	v_pk_mul_f32 v[56:57], v[86:87], v[56:57]
	v_lshlrev_b32_e32 v60, 16, v137
	v_and_b32_e32 v61, 0xffff0000, v137
	v_lshlrev_b32_e32 v58, 16, v127
	v_and_b32_e32 v59, 0xffff0000, v127
	v_pk_fma_f32 v[56:57], v[82:83], v[60:61], v[56:57]
	v_mov_b32_dpp v99, v139 row_ror:1 row_mask:0xf bank_mask:0xf
	v_pk_fma_f32 v[56:57], v[78:79], v[58:59], v[56:57]
	s_waitcnt lgkmcnt(0)
	v_cndmask_b32_e64 v128, v98, v140, s[6:7]
	v_pk_add_f32 v[56:57], v[56:57], 0 op_sel_hi:[1,0]
	v_cndmask_b32_e64 v129, v146, v120, s[8:9]
	v_pk_mul_f32 v[54:55], v[54:55], v[56:57]
	v_lshlrev_b32_e32 v56, 16, v128
	v_and_b32_e32 v57, 0xffff0000, v128
	v_pk_mul_f32 v[56:57], v[72:73], v[56:57]
	v_lshlrev_b32_e32 v60, 16, v138
	v_and_b32_e32 v61, 0xffff0000, v138
	v_lshlrev_b32_e32 v58, 16, v129
	v_and_b32_e32 v59, 0xffff0000, v129
	v_pk_fma_f32 v[56:57], v[68:69], v[60:61], v[56:57]
	s_waitcnt lgkmcnt(0)
	v_cndmask_b32_e64 v132, v99, v142, s[6:7]
	v_pk_fma_f32 v[56:57], v[64:65], v[58:59], v[56:57]
	v_cndmask_b32_e64 v133, v147, v121, s[8:9]
	v_pk_add_f32 v[56:57], v[56:57], 0 op_sel_hi:[1,0]
	v_lshlrev_b32_e32 v60, 16, v139
	v_pk_mul_f32 v[56:57], v[48:49], v[56:57]
	v_lshlrev_b32_e32 v48, 16, v132
	v_and_b32_e32 v49, 0xffff0000, v132
	v_pk_mul_f32 v[48:49], v[74:75], v[48:49]
	v_and_b32_e32 v61, 0xffff0000, v139
	v_lshlrev_b32_e32 v58, 16, v133
	v_and_b32_e32 v59, 0xffff0000, v133
	v_pk_fma_f32 v[48:49], v[70:71], v[60:61], v[48:49]
	s_waitcnt vmcnt(1)
	v_mov_b32_dpp v60, v90 row_ror:15 row_mask:0xf bank_mask:0xf
	v_pk_fma_f32 v[48:49], v[66:67], v[58:59], v[48:49]
	v_mov_b32_dpp v61, v91 row_ror:15 row_mask:0xf bank_mask:0xf
	v_pk_add_f32 v[48:49], v[48:49], 0 op_sel_hi:[1,0]
	v_cndmask_b32_e64 v125, v125, 0, s[14:15]
	v_pk_mul_f32 v[58:59], v[50:51], v[48:49]
	v_cvt_pk_bf16_f32 v49, v54, v55
	v_mov_b32_dpp v54, v92 row_ror:1 row_mask:0xf bank_mask:0xf
	v_cvt_pk_bf16_f32 v51, v58, v59
	v_mov_b32_dpp v58, v88 row_ror:15 row_mask:0xf bank_mask:0xf
	v_cvt_pk_bf16_f32 v48, v52, v53
	v_cvt_pk_bf16_f32 v50, v56, v57
	global_store_dwordx4 v[112:113], v[48:51], off offset:256
	v_mov_b32_dpp v55, v93 row_ror:1 row_mask:0xf bank_mask:0xf
	v_mov_b32_dpp v59, v89 row_ror:15 row_mask:0xf bank_mask:0xf
	s_waitcnt lgkmcnt(0)
	v_cndmask_b32_e64 v49, v54, v62, s[6:7]
	v_lshlrev_b32_e32 v48, 16, v49
	v_and_b32_e32 v49, 0xffff0000, v49
	s_waitcnt lgkmcnt(0)
	v_cndmask_b32_e64 v51, v102, v58, s[8:9]
	v_pk_mul_f32 v[48:49], v[84:85], v[48:49]
	v_lshlrev_b32_e32 v52, 16, v92
	v_and_b32_e32 v53, 0xffff0000, v92
	v_lshlrev_b32_e32 v50, 16, v51
	v_and_b32_e32 v51, 0xffff0000, v51
	v_pk_fma_f32 v[48:49], v[80:81], v[52:53], v[48:49]
	v_mov_b32_dpp v56, v94 row_ror:1 row_mask:0xf bank_mask:0xf
	v_pk_fma_f32 v[48:49], v[76:77], v[50:51], v[48:49]
	s_waitcnt lgkmcnt(0)
	v_cndmask_b32_e64 v62, v55, v63, s[6:7]
	v_pk_add_f32 v[48:49], v[48:49], 0 op_sel_hi:[1,0]
	s_waitcnt lgkmcnt(0)
	v_cndmask_b32_e64 v63, v103, v59, s[8:9]
	v_pk_mul_f32 v[44:45], v[44:45], v[48:49]
	v_lshlrev_b32_e32 v48, 16, v62
	v_and_b32_e32 v49, 0xffff0000, v62
	v_pk_mul_f32 v[48:49], v[86:87], v[48:49]
	v_lshlrev_b32_e32 v52, 16, v93
	v_and_b32_e32 v53, 0xffff0000, v93
	v_lshlrev_b32_e32 v50, 16, v63
	v_and_b32_e32 v51, 0xffff0000, v63
	v_pk_fma_f32 v[48:49], v[82:83], v[52:53], v[48:49]
	v_mov_b32_dpp v57, v95 row_ror:1 row_mask:0xf bank_mask:0xf
	v_pk_fma_f32 v[48:49], v[78:79], v[50:51], v[48:49]
	s_waitcnt lgkmcnt(0)
	v_cndmask_b32_e64 v98, v56, v98, s[6:7]
	v_pk_add_f32 v[48:49], v[48:49], 0 op_sel_hi:[1,0]
	v_cndmask_b32_e64 v102, v120, v60, s[8:9]
	v_pk_mul_f32 v[46:47], v[46:47], v[48:49]
	v_lshlrev_b32_e32 v48, 16, v98
	v_and_b32_e32 v49, 0xffff0000, v98
	v_pk_mul_f32 v[48:49], v[72:73], v[48:49]
	v_lshlrev_b32_e32 v52, 16, v94
	v_and_b32_e32 v53, 0xffff0000, v94
	v_lshlrev_b32_e32 v50, 16, v102
	v_and_b32_e32 v51, 0xffff0000, v102
	v_pk_fma_f32 v[48:49], v[68:69], v[52:53], v[48:49]
	s_waitcnt lgkmcnt(0)
	v_cndmask_b32_e64 v99, v57, v99, s[6:7]
	v_pk_fma_f32 v[48:49], v[64:65], v[50:51], v[48:49]
	v_cndmask_b32_e64 v103, v121, v61, s[8:9]
	v_pk_add_f32 v[48:49], v[48:49], 0 op_sel_hi:[1,0]
	v_lshlrev_b32_e32 v52, 16, v95
	v_pk_mul_f32 v[48:49], v[40:41], v[48:49]
	v_lshlrev_b32_e32 v40, 16, v99
	v_and_b32_e32 v41, 0xffff0000, v99
	v_pk_mul_f32 v[40:41], v[74:75], v[40:41]
	v_and_b32_e32 v53, 0xffff0000, v95
	v_lshlrev_b32_e32 v50, 16, v103
	v_and_b32_e32 v51, 0xffff0000, v103
	v_pk_fma_f32 v[40:41], v[70:71], v[52:53], v[40:41]
	s_nop 0
	v_pk_fma_f32 v[40:41], v[66:67], v[50:51], v[40:41]
	s_nop 0
	v_pk_add_f32 v[40:41], v[40:41], 0 op_sel_hi:[1,0]
	s_nop 0
	v_pk_mul_f32 v[50:51], v[42:43], v[40:41]
	v_cvt_pk_bf16_f32 v40, v44, v45
	v_cvt_pk_bf16_f32 v41, v46, v47
	v_cvt_pk_bf16_f32 v42, v48, v49
	v_cvt_pk_bf16_f32 v43, v50, v51
	v_mov_b32_dpp v44, v88 row_ror:1 row_mask:0xf bank_mask:0xf
	global_store_dwordx4 v[104:105], v[40:43], off offset:256
	ds_bpermute_b32 v40, v175, v89
	ds_bpermute_b32 v41, v175, v90
	v_mov_b32_dpp v42, v91 row_ror:1 row_mask:0xf bank_mask:0xf
	s_waitcnt lgkmcnt(0)
	v_cndmask_b32_e64 v43, v44, v54, s[6:7]
	v_cndmask_b32_e64 v44, v58, v124, s[8:9]
	s_waitcnt lgkmcnt(0)
	v_cndmask_b32_e64 v46, v40, v55, s[6:7]
	s_waitcnt lgkmcnt(0)
	v_cndmask_b32_e64 v48, v41, v56, s[6:7]
	v_lshlrev_b32_e32 v40, 16, v43
	v_and_b32_e32 v41, 0xffff0000, v43
	s_waitcnt lgkmcnt(0)
	v_cndmask_b32_e64 v50, v42, v57, s[6:7]
	v_lshlrev_b32_e32 v42, 16, v44
	v_and_b32_e32 v43, 0xffff0000, v44
	v_pk_mul_f32 v[40:41], v[84:85], v[40:41]
	v_lshlrev_b32_e32 v44, 16, v88
	v_and_b32_e32 v45, 0xffff0000, v88
	v_pk_fma_f32 v[40:41], v[80:81], v[44:45], v[40:41]
	v_cndmask_b32_e64 v47, v59, v125, s[8:9]
	v_pk_fma_f32 v[40:41], v[76:77], v[42:43], v[40:41]
	v_lshlrev_b32_e32 v44, 16, v89
	v_pk_add_f32 v[40:41], v[40:41], 0 op_sel_hi:[1,0]
	v_and_b32_e32 v45, 0xffff0000, v89
	v_pk_mul_f32 v[36:37], v[36:37], v[40:41]
	v_lshlrev_b32_e32 v40, 16, v46
	v_and_b32_e32 v41, 0xffff0000, v46
	v_pk_mul_f32 v[40:41], v[86:87], v[40:41]
	v_lshlrev_b32_e32 v42, 16, v47
	v_and_b32_e32 v43, 0xffff0000, v47
	v_pk_fma_f32 v[40:41], v[82:83], v[44:45], v[40:41]
	v_cndmask_b32_e64 v49, v60, v123, s[8:9]
	v_pk_fma_f32 v[40:41], v[78:79], v[42:43], v[40:41]
	v_lshlrev_b32_e32 v44, 16, v90
	v_pk_add_f32 v[40:41], v[40:41], 0 op_sel_hi:[1,0]
	v_and_b32_e32 v45, 0xffff0000, v90
	v_pk_mul_f32 v[38:39], v[38:39], v[40:41]
	v_lshlrev_b32_e32 v40, 16, v48
	v_and_b32_e32 v41, 0xffff0000, v48
	v_pk_mul_f32 v[40:41], v[72:73], v[40:41]
	v_lshlrev_b32_e32 v42, 16, v49
	v_and_b32_e32 v43, 0xffff0000, v49
	v_pk_fma_f32 v[40:41], v[68:69], v[44:45], v[40:41]
	v_cndmask_b32_e64 v51, v61, v122, s[8:9]
	v_pk_fma_f32 v[40:41], v[64:65], v[42:43], v[40:41]
	v_lshlrev_b32_e32 v44, 16, v91
	v_pk_add_f32 v[40:41], v[40:41], 0 op_sel_hi:[1,0]
	v_and_b32_e32 v45, 0xffff0000, v91
	v_pk_mul_f32 v[40:41], v[32:33], v[40:41]
	v_lshlrev_b32_e32 v32, 16, v50
	v_and_b32_e32 v33, 0xffff0000, v50
	v_pk_mul_f32 v[32:33], v[74:75], v[32:33]
	v_lshlrev_b32_e32 v42, 16, v51
	v_and_b32_e32 v43, 0xffff0000, v51
	v_pk_fma_f32 v[32:33], v[70:71], v[44:45], v[32:33]
	s_nop 0
	v_pk_fma_f32 v[32:33], v[66:67], v[42:43], v[32:33]
	s_nop 0
	v_pk_add_f32 v[32:33], v[32:33], 0 op_sel_hi:[1,0]
	s_nop 0
	v_pk_mul_f32 v[42:43], v[34:35], v[32:33]
	v_cvt_pk_bf16_f32 v32, v36, v37
	v_cvt_pk_bf16_f32 v33, v38, v39
	v_cvt_pk_bf16_f32 v34, v40, v41
	v_cvt_pk_bf16_f32 v35, v42, v43
	global_store_dwordx4 v[106:107], v[32:35], off offset:256
	global_load_dwordx4 v[44:47], v[108:109], off offset:256
	global_load_dwordx4 v[48:51], v[114:115], off offset:256
	global_load_dwordx4 v[52:55], v[116:117], off offset:256
	global_load_dwordx4 v[40:43], v[118:119], off offset:256
	global_load_dwordx4 v[32:35], v[130:131], off offset:256
	global_load_dwordx4 v[36:39], v[110:111], off offset:256
	s_waitcnt vmcnt(5)
	v_cndmask_b32_e64 v44, v44, 0, s[22:23]
	s_waitcnt vmcnt(4)
	v_mov_b32_dpp v58, v48 row_ror:1 row_mask:0xf bank_mask:0xf
	v_mov_b32_dpp v56, v48 row_ror:15 row_mask:0xf bank_mask:0xf
	v_mov_b32_dpp v59, v49 row_ror:1 row_mask:0xf bank_mask:0xf
	s_waitcnt vmcnt(3)
	v_mov_b32_dpp v88, v52 row_ror:15 row_mask:0xf bank_mask:0xf
	v_mov_b32_dpp v57, v49 row_ror:15 row_mask:0xf bank_mask:0xf
	v_mov_b32_dpp v60, v50 row_ror:1 row_mask:0xf bank_mask:0xf
	v_mov_b32_dpp v62, v51 row_ror:1 row_mask:0xf bank_mask:0xf
	v_mov_b32_dpp v89, v53 row_ror:15 row_mask:0xf bank_mask:0xf
	v_cndmask_b32_e64 v45, v45, 0, s[22:23]
	s_waitcnt lgkmcnt(0)
	v_cndmask_b32_e64 v92, v58, v44, s[6:7]
	v_cndmask_b32_e64 v47, v47, 0, s[22:23]
	v_cndmask_b32_e64 v46, v46, 0, s[22:23]
	s_waitcnt lgkmcnt(0)
	v_cndmask_b32_e64 v56, v56, v88, s[8:9]
	v_cndmask_b32_e64 v93, v59, v45, s[6:7]
	v_lshlrev_b32_e32 v44, 16, v92
	v_and_b32_e32 v45, 0xffff0000, v92
	s_waitcnt lgkmcnt(0)
	v_cndmask_b32_e64 v94, v57, v89, s[8:9]
	v_cndmask_b32_e64 v95, v60, v46, s[6:7]
	v_cndmask_b32_e64 v98, v62, v47, s[6:7]
	v_lshlrev_b32_e32 v46, 16, v56
	v_and_b32_e32 v47, 0xffff0000, v56
	v_pk_mul_f32 v[44:45], v[84:85], v[44:45]
	v_lshlrev_b32_e32 v56, 16, v48
	v_and_b32_e32 v57, 0xffff0000, v48
	v_pk_fma_f32 v[44:45], v[80:81], v[56:57], v[44:45]
	v_mov_b32_dpp v61, v50 row_ror:15 row_mask:0xf bank_mask:0xf
	v_pk_fma_f32 v[44:45], v[76:77], v[46:47], v[44:45]
	v_mov_b32_dpp v90, v54 row_ror:15 row_mask:0xf bank_mask:0xf
	v_pk_add_f32 v[44:45], v[44:45], 0 op_sel_hi:[1,0]
	v_lshlrev_b32_e32 v48, 16, v49
	v_pk_mul_f32 v[28:29], v[28:29], v[44:45]
	v_lshlrev_b32_e32 v44, 16, v93
	v_and_b32_e32 v45, 0xffff0000, v93
	v_pk_mul_f32 v[44:45], v[86:87], v[44:45]
	v_and_b32_e32 v49, 0xffff0000, v49
	v_lshlrev_b32_e32 v46, 16, v94
	v_and_b32_e32 v47, 0xffff0000, v94
	v_pk_fma_f32 v[44:45], v[82:83], v[48:49], v[44:45]
	v_mov_b32_dpp v63, v51 row_ror:15 row_mask:0xf bank_mask:0xf
	v_pk_fma_f32 v[44:45], v[78:79], v[46:47], v[44:45]
	v_mov_b32_dpp v91, v55 row_ror:15 row_mask:0xf bank_mask:0xf
	v_pk_add_f32 v[44:45], v[44:45], 0 op_sel_hi:[1,0]
	s_waitcnt lgkmcnt(0)
	v_cndmask_b32_e64 v61, v61, v90, s[8:9]
	v_pk_mul_f32 v[30:31], v[30:31], v[44:45]
	v_lshlrev_b32_e32 v44, 16, v95
	v_and_b32_e32 v45, 0xffff0000, v95
	v_pk_mul_f32 v[44:45], v[72:73], v[44:45]
	v_lshlrev_b32_e32 v48, 16, v50
	v_and_b32_e32 v49, 0xffff0000, v50
	v_lshlrev_b32_e32 v46, 16, v61
	v_and_b32_e32 v47, 0xffff0000, v61
	v_pk_fma_f32 v[44:45], v[68:69], v[48:49], v[44:45]
	s_waitcnt lgkmcnt(0)
	v_cndmask_b32_e64 v63, v63, v91, s[8:9]
	v_pk_fma_f32 v[44:45], v[64:65], v[46:47], v[44:45]
	v_lshlrev_b32_e32 v48, 16, v51
	v_pk_add_f32 v[44:45], v[44:45], 0 op_sel_hi:[1,0]
	v_and_b32_e32 v49, 0xffff0000, v51
	v_pk_mul_f32 v[44:45], v[24:25], v[44:45]
	v_lshlrev_b32_e32 v24, 16, v98
	v_and_b32_e32 v25, 0xffff0000, v98
	v_pk_mul_f32 v[24:25], v[74:75], v[24:25]
	v_lshlrev_b32_e32 v46, 16, v63
	v_and_b32_e32 v47, 0xffff0000, v63
	v_pk_fma_f32 v[24:25], v[70:71], v[48:49], v[24:25]
	s_waitcnt vmcnt(2)
	v_mov_b32_dpp v48, v42 row_ror:15 row_mask:0xf bank_mask:0xf
	v_pk_fma_f32 v[24:25], v[66:67], v[46:47], v[24:25]
	v_mov_b32_dpp v49, v43 row_ror:15 row_mask:0xf bank_mask:0xf
	v_pk_add_f32 v[24:25], v[24:25], 0 op_sel_hi:[1,0]
	s_waitcnt lgkmcnt(0)
	v_cndmask_b32_e64 v57, v90, v48, s[8:9]
	v_pk_mul_f32 v[46:47], v[26:27], v[24:25]
	v_cvt_pk_bf16_f32 v25, v30, v31
	v_mov_b32_dpp v30, v52 row_ror:1 row_mask:0xf bank_mask:0xf
	v_cvt_pk_bf16_f32 v27, v46, v47
	v_mov_b32_dpp v46, v40 row_ror:15 row_mask:0xf bank_mask:0xf
	v_cvt_pk_bf16_f32 v24, v28, v29
	v_cvt_pk_bf16_f32 v26, v44, v45
	global_store_dwordx4 v[148:149], v[24:27], off offset:256
	v_mov_b32_dpp v31, v53 row_ror:1 row_mask:0xf bank_mask:0xf
	v_mov_b32_dpp v47, v41 row_ror:15 row_mask:0xf bank_mask:0xf
	s_waitcnt lgkmcnt(0)
	v_cndmask_b32_e64 v25, v30, v58, s[6:7]
	v_lshlrev_b32_e32 v24, 16, v25
	v_and_b32_e32 v25, 0xffff0000, v25
	s_waitcnt lgkmcnt(0)
	v_cndmask_b32_e64 v27, v88, v46, s[8:9]
	v_pk_mul_f32 v[24:25], v[84:85], v[24:25]
	v_lshlrev_b32_e32 v28, 16, v52
	v_and_b32_e32 v29, 0xffff0000, v52
	v_lshlrev_b32_e32 v26, 16, v27
	v_and_b32_e32 v27, 0xffff0000, v27
	v_pk_fma_f32 v[24:25], v[80:81], v[28:29], v[24:25]
	v_mov_b32_dpp v44, v54 row_ror:1 row_mask:0xf bank_mask:0xf
	v_pk_fma_f32 v[24:25], v[76:77], v[26:27], v[24:25]
	s_waitcnt lgkmcnt(0)
	v_cndmask_b32_e64 v50, v31, v59, s[6:7]
	v_pk_add_f32 v[24:25], v[24:25], 0 op_sel_hi:[1,0]
	s_waitcnt lgkmcnt(0)
	v_cndmask_b32_e64 v51, v89, v47, s[8:9]
	v_pk_mul_f32 v[20:21], v[20:21], v[24:25]
	v_lshlrev_b32_e32 v24, 16, v50
	v_and_b32_e32 v25, 0xffff0000, v50
	v_pk_mul_f32 v[24:25], v[86:87], v[24:25]
	v_lshlrev_b32_e32 v28, 16, v53
	v_and_b32_e32 v29, 0xffff0000, v53
	v_lshlrev_b32_e32 v26, 16, v51
	v_and_b32_e32 v27, 0xffff0000, v51
	v_pk_fma_f32 v[24:25], v[82:83], v[28:29], v[24:25]
	v_mov_b32_dpp v45, v55 row_ror:1 row_mask:0xf bank_mask:0xf
	v_pk_fma_f32 v[24:25], v[78:79], v[26:27], v[24:25]
	s_waitcnt lgkmcnt(0)
	v_cndmask_b32_e64 v56, v44, v60, s[6:7]
	v_pk_add_f32 v[24:25], v[24:25], 0 op_sel_hi:[1,0]
	v_lshlrev_b32_e32 v28, 16, v54
	v_pk_mul_f32 v[22:23], v[22:23], v[24:25]
	v_lshlrev_b32_e32 v24, 16, v56
	v_and_b32_e32 v25, 0xffff0000, v56
	v_pk_mul_f32 v[24:25], v[72:73], v[24:25]
	v_and_b32_e32 v29, 0xffff0000, v54
	v_lshlrev_b32_e32 v26, 16, v57
	v_and_b32_e32 v27, 0xffff0000, v57
	v_pk_fma_f32 v[24:25], v[68:69], v[28:29], v[24:25]
	s_waitcnt lgkmcnt(0)
	v_cndmask_b32_e64 v58, v45, v62, s[6:7]
	v_pk_fma_f32 v[24:25], v[64:65], v[26:27], v[24:25]
	v_cndmask_b32_e64 v59, v91, v49, s[8:9]
	v_pk_add_f32 v[24:25], v[24:25], 0 op_sel_hi:[1,0]
	v_lshlrev_b32_e32 v28, 16, v55
	v_pk_mul_f32 v[24:25], v[16:17], v[24:25]
	v_lshlrev_b32_e32 v16, 16, v58
	v_and_b32_e32 v17, 0xffff0000, v58
	v_pk_mul_f32 v[16:17], v[74:75], v[16:17]
	v_and_b32_e32 v29, 0xffff0000, v55
	v_lshlrev_b32_e32 v26, 16, v59
	v_and_b32_e32 v27, 0xffff0000, v59
	v_pk_fma_f32 v[16:17], v[70:71], v[28:29], v[16:17]
	s_waitcnt vmcnt(2)
	v_mov_b32_dpp v28, v34 row_ror:15 row_mask:0xf bank_mask:0xf
	v_pk_fma_f32 v[16:17], v[66:67], v[26:27], v[16:17]
	v_mov_b32_dpp v29, v35 row_ror:15 row_mask:0xf bank_mask:0xf
	v_pk_add_f32 v[16:17], v[16:17], 0 op_sel_hi:[1,0]
	s_nop 0
	v_pk_mul_f32 v[26:27], v[18:19], v[16:17]
	v_cvt_pk_bf16_f32 v17, v22, v23
	v_mov_b32_dpp v22, v40 row_ror:1 row_mask:0xf bank_mask:0xf
	v_cvt_pk_bf16_f32 v19, v26, v27
	v_mov_b32_dpp v26, v32 row_ror:15 row_mask:0xf bank_mask:0xf
	v_cvt_pk_bf16_f32 v16, v20, v21
	v_cvt_pk_bf16_f32 v18, v24, v25
	global_store_dwordx4 v[150:151], v[16:19], off offset:256
	v_mov_b32_dpp v23, v41 row_ror:1 row_mask:0xf bank_mask:0xf
	v_mov_b32_dpp v27, v33 row_ror:15 row_mask:0xf bank_mask:0xf
	s_waitcnt lgkmcnt(0)
	v_cndmask_b32_e64 v17, v22, v30, s[6:7]
	v_lshlrev_b32_e32 v16, 16, v17
	v_and_b32_e32 v17, 0xffff0000, v17
	s_waitcnt lgkmcnt(0)
	v_cndmask_b32_e64 v19, v46, v26, s[8:9]
	v_pk_mul_f32 v[16:17], v[84:85], v[16:17]
	v_lshlrev_b32_e32 v20, 16, v40
	v_and_b32_e32 v21, 0xffff0000, v40
	v_lshlrev_b32_e32 v18, 16, v19
	v_and_b32_e32 v19, 0xffff0000, v19
	v_pk_fma_f32 v[16:17], v[80:81], v[20:21], v[16:17]
	v_mov_b32_dpp v24, v42 row_ror:1 row_mask:0xf bank_mask:0xf
	v_pk_fma_f32 v[16:17], v[76:77], v[18:19], v[16:17]
	s_waitcnt lgkmcnt(0)
	v_cndmask_b32_e64 v30, v23, v31, s[6:7]
	v_pk_add_f32 v[16:17], v[16:17], 0 op_sel_hi:[1,0]
	s_waitcnt lgkmcnt(0)
	v_cndmask_b32_e64 v31, v47, v27, s[8:9]
	v_pk_mul_f32 v[12:13], v[12:13], v[16:17]
	v_lshlrev_b32_e32 v16, 16, v30
	v_and_b32_e32 v17, 0xffff0000, v30
	v_pk_mul_f32 v[16:17], v[86:87], v[16:17]
	v_lshlrev_b32_e32 v20, 16, v41
	v_and_b32_e32 v21, 0xffff0000, v41
	v_lshlrev_b32_e32 v18, 16, v31
	v_and_b32_e32 v19, 0xffff0000, v31
	v_pk_fma_f32 v[16:17], v[82:83], v[20:21], v[16:17]
	v_mov_b32_dpp v25, v43 row_ror:1 row_mask:0xf bank_mask:0xf
	v_pk_fma_f32 v[16:17], v[78:79], v[18:19], v[16:17]
	s_waitcnt lgkmcnt(0)
	v_cndmask_b32_e64 v44, v24, v44, s[6:7]
	v_pk_add_f32 v[16:17], v[16:17], 0 op_sel_hi:[1,0]
	v_cndmask_b32_e64 v46, v48, v28, s[8:9]
	v_pk_mul_f32 v[14:15], v[14:15], v[16:17]
	v_lshlrev_b32_e32 v16, 16, v44
	v_and_b32_e32 v17, 0xffff0000, v44
	v_pk_mul_f32 v[16:17], v[72:73], v[16:17]
	v_lshlrev_b32_e32 v20, 16, v42
	v_and_b32_e32 v21, 0xffff0000, v42
	v_lshlrev_b32_e32 v18, 16, v46
	v_and_b32_e32 v19, 0xffff0000, v46
	v_pk_fma_f32 v[16:17], v[68:69], v[20:21], v[16:17]
	s_waitcnt lgkmcnt(0)
	v_cndmask_b32_e64 v45, v25, v45, s[6:7]
	v_pk_fma_f32 v[16:17], v[64:65], v[18:19], v[16:17]
	v_cndmask_b32_e64 v47, v49, v29, s[8:9]
	v_pk_add_f32 v[16:17], v[16:17], 0 op_sel_hi:[1,0]
	v_lshlrev_b32_e32 v20, 16, v43
	v_pk_mul_f32 v[16:17], v[8:9], v[16:17]
	v_lshlrev_b32_e32 v8, 16, v45
	v_and_b32_e32 v9, 0xffff0000, v45
	v_pk_mul_f32 v[8:9], v[74:75], v[8:9]
	v_and_b32_e32 v21, 0xffff0000, v43
	v_lshlrev_b32_e32 v18, 16, v47
	v_and_b32_e32 v19, 0xffff0000, v47
	v_pk_fma_f32 v[8:9], v[70:71], v[20:21], v[8:9]
	s_nop 0
	v_pk_fma_f32 v[8:9], v[66:67], v[18:19], v[8:9]
	s_nop 0
	v_pk_add_f32 v[8:9], v[8:9], 0 op_sel_hi:[1,0]
	s_nop 0
	v_pk_mul_f32 v[18:19], v[10:11], v[8:9]
	v_cvt_pk_bf16_f32 v8, v12, v13
	v_cvt_pk_bf16_f32 v9, v14, v15
	v_cvt_pk_bf16_f32 v10, v16, v17
	v_cvt_pk_bf16_f32 v11, v18, v19
	global_store_dwordx4 v[100:101], v[8:11], off offset:256
	ds_bpermute_b32 v8, v175, v32
	ds_bpermute_b32 v9, v175, v33
	v_mov_b32_dpp v10, v34 row_ror:1 row_mask:0xf bank_mask:0xf
	v_mov_b32_dpp v11, v35 row_ror:1 row_mask:0xf bank_mask:0xf
	s_waitcnt vmcnt(3)
	v_cndmask_b32_e64 v12, v39, 0, s[0:1]
	s_waitcnt lgkmcnt(0)
	v_cndmask_b32_e64 v16, v8, v22, s[6:7]
	v_cndmask_b32_e64 v13, v38, 0, s[0:1]
	v_cndmask_b32_e64 v15, v36, 0, s[0:1]
	s_waitcnt lgkmcnt(0)
	v_cndmask_b32_e64 v17, v9, v23, s[6:7]
	v_lshlrev_b32_e32 v8, 16, v16
	v_and_b32_e32 v9, 0xffff0000, v16
	v_cndmask_b32_e64 v15, v26, v15, s[8:9]
	v_cndmask_b32_e64 v19, v28, v13, s[8:9]
	v_cndmask_b32_e64 v21, v29, v12, s[8:9]
	v_pk_mul_f32 v[8:9], v[84:85], v[8:9]
	v_lshlrev_b32_e32 v12, 16, v32
	v_and_b32_e32 v13, 0xffff0000, v32
	s_waitcnt lgkmcnt(0)
	v_cndmask_b32_e64 v18, v10, v24, s[6:7]
	s_waitcnt lgkmcnt(0)
	v_cndmask_b32_e64 v20, v11, v25, s[6:7]
	v_lshlrev_b32_e32 v10, 16, v15
	v_and_b32_e32 v11, 0xffff0000, v15
	v_pk_fma_f32 v[8:9], v[80:81], v[12:13], v[8:9]
	v_cndmask_b32_e64 v14, v37, 0, s[0:1]
	v_pk_fma_f32 v[8:9], v[76:77], v[10:11], v[8:9]
	v_cndmask_b32_e64 v14, v27, v14, s[8:9]
	v_pk_add_f32 v[8:9], v[8:9], 0 op_sel_hi:[1,0]
	v_lshlrev_b32_e32 v12, 16, v33
	v_pk_mul_f32 v[4:5], v[4:5], v[8:9]
	v_lshlrev_b32_e32 v8, 16, v17
	v_and_b32_e32 v9, 0xffff0000, v17
	v_pk_mul_f32 v[8:9], v[86:87], v[8:9]
	v_and_b32_e32 v13, 0xffff0000, v33
	v_lshlrev_b32_e32 v10, 16, v14
	v_and_b32_e32 v11, 0xffff0000, v14
	v_pk_fma_f32 v[8:9], v[82:83], v[12:13], v[8:9]
	v_lshlrev_b32_e32 v12, 16, v34
	v_pk_fma_f32 v[8:9], v[78:79], v[10:11], v[8:9]
	v_and_b32_e32 v13, 0xffff0000, v34
	v_pk_add_f32 v[8:9], v[8:9], 0 op_sel_hi:[1,0]
	v_lshlrev_b32_e32 v10, 16, v19
	v_pk_mul_f32 v[6:7], v[6:7], v[8:9]
	v_lshlrev_b32_e32 v8, 16, v18
	v_and_b32_e32 v9, 0xffff0000, v18
	v_pk_mul_f32 v[8:9], v[72:73], v[8:9]
	v_and_b32_e32 v11, 0xffff0000, v19
	v_pk_fma_f32 v[8:9], v[68:69], v[12:13], v[8:9]
	v_lshlrev_b32_e32 v12, 16, v35
	v_pk_fma_f32 v[8:9], v[64:65], v[10:11], v[8:9]
	v_and_b32_e32 v13, 0xffff0000, v35
	v_pk_add_f32 v[8:9], v[8:9], 0 op_sel_hi:[1,0]
	v_lshlrev_b32_e32 v10, 16, v21
	v_pk_mul_f32 v[8:9], v[0:1], v[8:9]
	v_lshlrev_b32_e32 v0, 16, v20
	v_and_b32_e32 v1, 0xffff0000, v20
	v_pk_mul_f32 v[0:1], v[74:75], v[0:1]
	v_and_b32_e32 v11, 0xffff0000, v21
	v_pk_fma_f32 v[0:1], v[70:71], v[12:13], v[0:1]
	s_mov_b64 s[0:1], -1
	v_pk_fma_f32 v[0:1], v[66:67], v[10:11], v[0:1]
	s_nop 0
	v_pk_add_f32 v[0:1], v[0:1], 0 op_sel_hi:[1,0]
	s_nop 0
	v_pk_mul_f32 v[10:11], v[2:3], v[0:1]
	v_cvt_pk_bf16_f32 v0, v4, v5
	v_cvt_pk_bf16_f32 v1, v6, v7
	v_cvt_pk_bf16_f32 v2, v8, v9
	v_cvt_pk_bf16_f32 v3, v10, v11
	global_store_dwordx4 v[96:97], v[0:3], off offset:256
	s_cbranch_vccnz .LBB0_204
	s_andn2_b64 vcc, exec, s[18:19]
	s_cbranch_vccnz .LBB0_203
	s_barrier
	s_branch .LBB0_203
